# P9: the 11-unit workgroups (cid 120..239) start 15us late (slack) to interleave epilogue bursts
# baseline (speedup 1.0000x reference)
.LBB0_1204:
	v_readlane_b32 s10, v246, 4
	s_cmp_lt_i32 s10, 10
	s_cselect_b64 s[0:1], -1, 0
	s_and_b64 s[2:3], s[0:1], s[2:3]
	v_readlane_b32 s11, v246, 5
	s_andn2_b64 vcc, exec, s[2:3]
	s_cbranch_vccnz .LBB0_1272
	s_cmpk_lt_u32 s30, 0x78
	s_cbranch_scc1 .Lstg9_done
	s_cmpk_gt_u32 s30, 0xef
	s_cbranch_scc1 .Lstg9_done
	s_sleep 127
	s_sleep 127
	s_sleep 127
	s_sleep 127
.Lstg9_done:
	v_readlane_b32 s2, v244, 58
	v_readlane_b32 s3, v244, 59
	v_readfirstlane_b32 s33, v202
	s_and_b64 vcc, exec, s[2:3]
	s_cbranch_vccz .LBB0_1207
	s_ashr_i32 s31, s30, 31
	s_mov_b64 s[4:5], s[30:31]
	s_cbranch_execz .LBB0_1208
	s_branch .LBB0_1212
